# prologue rmsnorm row loop: hoisted the 8 loop-invariant gain vector loads (each was load + vmcnt(0), also draining the next-row prefetch) out of the loop into registers
# speedup vs baseline: 1.0163x; 1.0099x over previous
; #define LAS __attribute__((address_space(3)))
; __device__ __forceinline__ unsigned pk2(float lo, float hi) { return pg8::cvt_pk_bf16(lo, hi); }
; __device__ __forceinline__ void rms_row_loaded(const float* __restrict__ g, bf16_t* orow, int lane, f32x4 (&v)[8]) {
;     ...
;     const f32x4* gr = (const f32x4*)g + lane;
;     u32x2* o8 = (u32x2*)orow + lane;
; #pragma unroll
;     for (int j = 0; j < 8; ++j) { v[j] = v[j] * rstd * gr[64 * j]; u32x2 w; w.x = pk2(v[j].x, v[j].y); w.y = pk2(v[j].z, v[j].w); o8[64 * j] = w; }
; __device__ __forceinline__ void prologue_phase(const Ptrs& P, LAS unsigned char* lds, int vcu, int G, int tid, int lane, int wave) {
;     ...
;     LAS float* wg = (LAS float*)lds;
;     for (int i = tid; i < DM * 8; i += 512) wg[i] = P.in[2][(size_t)(i >> 3) * IN0 + PROJW + (i & 7)];
;     __syncthreads();
;     bf16_t* XN = (bf16_t*)(ws + WS_XN); float* gates = (float*)(ws + WS_GATES);
;     f32x4 vn[8];
;     if (gw < MTOK) { const f32x4* xr = (const f32x4*)(P.in[0] + (size_t)gw * DM) + lane;
; #pragma unroll
;         for (int j = 0; j < 8; ++j) vn[j] = xr[64 * j]; }
;     for (int m = gw; m < MTOK; m += NGW) {
;         f32x4 v[8];
; #pragma unroll
;         for (int j = 0; j < 8; ++j) v[j] = vn[j];
;         if (m + NGW < MTOK) { const f32x4* xr = (const f32x4*)(P.in[0] + (size_t)(m + NGW) * DM) + lane;
; #pragma unroll
;             for (int j = 0; j < 8; ++j) vn[j] = xr[64 * j]; }
.LBB0_49:
	s_or_b64 exec, exec, s[0:1]
	s_cmpk_lt_i32 s40, 0x4000
	v_mbcnt_lo_u32_b32 v205, -1, 0
	s_waitcnt lgkmcnt(0)
	s_barrier
	s_cbranch_scc0 .LBB0_56
	s_ashr_i32 s41, s40, 31
	s_lshl_b64 s[0:1], s[40:41], 13
	s_add_u32 s0, s20, s0
	s_addc_u32 s1, s21, s1
	v_lshlrev_b32_e32 v66, 4, v1
	v_mov_b32_e32 v67, 0
	v_lshl_add_u64 v[2:3], s[0:1], 0, v[66:67]
	s_movk_i32 s3, 0x1000
	v_add_co_u32_e32 v2, vcc, s3, v2
	v_lshl_add_u64 v[68:69], s[22:23], 0, v[66:67]
	s_nop 0
	v_addc_co_u32_e32 v3, vcc, 0, v3, vcc
	global_load_dwordx4 v[34:37], v[2:3], off offset:3072
	global_load_dwordx4 v[38:41], v[2:3], off offset:2048
	global_load_dwordx4 v[42:45], v[2:3], off offset:1024
	global_load_dwordx4 v[46:49], v[2:3], off
	global_load_dwordx4 v[50:53], v66, s[0:1] offset:3072
	global_load_dwordx4 v[54:57], v66, s[0:1] offset:2048
	global_load_dwordx4 v[58:61], v66, s[0:1] offset:1024
	global_load_dwordx4 v[62:65], v66, s[0:1]
	v_mbcnt_hi_u32_b32 v2, -1, v205
	v_and_b32_e32 v3, 64, v2
	v_add_u32_e32 v3, 64, v3
	v_xor_b32_e32 v4, 1, v2
	v_cmp_lt_i32_e32 vcc, v4, v3
	s_mov_b64 s[8:9], 0x1400
	v_lshl_add_u64 v[72:73], v[68:69], 0, s[8:9]
	v_cndmask_b32_e32 v4, v2, v4, vcc
	v_lshlrev_b32_e32 v84, 2, v4
	v_xor_b32_e32 v4, 2, v2
	v_cmp_lt_i32_e32 vcc, v4, v3
	s_mov_b64 s[8:9], 0x1800
	v_lshl_add_u64 v[74:75], v[68:69], 0, s[8:9]
	v_cndmask_b32_e32 v4, v2, v4, vcc
	v_lshlrev_b32_e32 v85, 2, v4
	v_xor_b32_e32 v4, 4, v2
	v_cmp_lt_i32_e32 vcc, v4, v3
	s_mov_b64 s[8:9], 0x1c00
	v_lshl_add_u64 v[76:77], v[68:69], 0, s[8:9]
	v_cndmask_b32_e32 v4, v2, v4, vcc
	v_lshlrev_b32_e32 v86, 2, v4
	v_xor_b32_e32 v4, 8, v2
	v_cmp_lt_i32_e32 vcc, v4, v3
	v_readlane_b32 s8, v247, 0
	s_ashr_i32 s3, s2, 31
	v_cndmask_b32_e32 v4, v2, v4, vcc
	s_ashr_i32 s7, s8, 31
	v_lshlrev_b32_e32 v87, 2, v4
	v_xor_b32_e32 v4, 16, v2
	s_add_u32 s2, s2, s8
	v_cmp_lt_i32_e32 vcc, v4, v3
	s_addc_u32 s3, s3, s7
	s_add_i32 s12, s40, s28
	v_cndmask_b32_e32 v4, v2, v4, vcc
	s_ashr_i32 s29, s28, 31
	s_ashr_i32 s13, s12, 31
	v_lshlrev_b32_e32 v88, 2, v4
	v_xor_b32_e32 v4, 32, v2
	s_lshl_b64 s[8:9], s[2:3], 5
	s_lshl_b64 s[10:11], s[28:29], 5
	s_lshl_b64 s[12:13], s[12:13], 13
	v_cmp_lt_i32_e32 vcc, v4, v3
	s_add_u32 s12, s20, s12
	s_addc_u32 s13, s21, s13
	v_cndmask_b32_e32 v2, v2, v4, vcc
	v_lshlrev_b32_e32 v89, 2, v2
	s_mov_b64 s[4:5], 0x1000
	v_lshl_add_u64 v[2:3], s[12:13], 0, v[66:67]
	s_lshl_b64 s[2:3], s[2:3], 12
	v_lshl_add_u64 v[78:79], v[2:3], 0, s[4:5]
	v_lshl_or_b32 v2, v1, 3, s2
	v_mov_b32_e32 v3, s3
	s_mov_b64 s[2:3], 0xd080800
	v_lshl_add_u64 v[80:81], v[2:3], 0, s[2:3]
	v_cmp_eq_u32_e64 s[0:1], 0, v1
	v_lshl_add_u32 v90, v1, 7, 0
	v_lshl_add_u64 v[70:71], v[68:69], 0, s[4:5]
	s_lshl_b64 s[12:13], s[28:29], 13
	s_lshl_b64 s[14:15], s[28:29], 12
	v_mov_b32_e32 v1, 0x358637bd
	s_mov_b32 s2, 0xf800000
	v_mov_b32_e32 v66, 0x260
	v_mov_b32_e32 v91, 0x400000
	s_waitcnt vmcnt(7)
	v_mov_b64_e32 v[2:3], v[34:35]
	s_waitcnt vmcnt(6)
	v_mov_b64_e32 v[6:7], v[38:39]
	s_waitcnt vmcnt(5)
	v_mov_b64_e32 v[10:11], v[42:43]
	s_waitcnt vmcnt(4)
	v_mov_b64_e32 v[14:15], v[46:47]
	s_waitcnt vmcnt(3)
	v_mov_b64_e32 v[18:19], v[50:51]
	s_waitcnt vmcnt(2)
	v_mov_b64_e32 v[22:23], v[54:55]
	s_waitcnt vmcnt(1)
	v_mov_b64_e32 v[26:27], v[58:59]
	s_waitcnt vmcnt(0)
	v_mov_b64_e32 v[30:31], v[62:63]
	v_mov_b64_e32 v[4:5], v[36:37]
	v_mov_b64_e32 v[8:9], v[40:41]
	v_mov_b64_e32 v[12:13], v[44:45]
	v_mov_b64_e32 v[16:17], v[48:49]
	v_mov_b64_e32 v[20:21], v[52:53]
	v_mov_b64_e32 v[24:25], v[56:57]
	v_mov_b64_e32 v[28:29], v[60:61]
	v_mov_b64_e32 v[32:33], v[64:65]
	global_load_dwordx4 v[116:119], v[68:69], off
	global_load_dwordx4 v[120:123], v[68:69], off offset:1024
	global_load_dwordx4 v[124:127], v[68:69], off offset:2048
	global_load_dwordx4 v[128:131], v[68:69], off offset:3072
	global_load_dwordx4 v[132:135], v[70:71], off
	global_load_dwordx4 v[136:139], v[72:73], off
	global_load_dwordx4 v[140:143], v[74:75], off
	global_load_dwordx4 v[144:147], v[76:77], off
	s_waitcnt vmcnt(0)
	s_branch .LBB0_52

; __device__ __forceinline__ unsigned pk2(float lo, float hi) { return pg8::cvt_pk_bf16(lo, hi); }
; __device__ __forceinline__ void rms_row_loaded(const float* __restrict__ g, bf16_t* orow, int lane, f32x4 (&v)[8]) {
;     float s = 0.f;
; #pragma unroll
;     for (int j = 0; j < 8; ++j) s += (v[j].x * v[j].x + v[j].y * v[j].y) + (v[j].z * v[j].z + v[j].w * v[j].w);
;     const float rstd = 1.0f / sqrtf(wave_sum(s) * (1.0f / DM) + EPS);
;     const f32x4* gr = (const f32x4*)g + lane;
;     u32x2* o8 = (u32x2*)orow + lane;
; #pragma unroll
;     for (int j = 0; j < 8; ++j) { v[j] = v[j] * rstd * gr[64 * j]; u32x2 w; w.x = pk2(v[j].x, v[j].y); w.y = pk2(v[j].z, v[j].w); o8[64 * j] = w; }
.LBB0_54:
	v_mov_b32_e32 v92, v59
	v_mov_b32_e32 v93, v63
	v_mov_b32_e32 v82, v58
	v_mov_b32_e32 v83, v62
	v_pk_mul_f32 v[92:93], v[92:93], v[92:93]
	v_mov_b32_e32 v94, v61
	v_mov_b32_e32 v95, v65
	v_pk_fma_f32 v[82:83], v[82:83], v[82:83], v[92:93]
	v_mov_b32_e32 v92, v60
	v_mov_b32_e32 v93, v64
	v_pk_mul_f32 v[94:95], v[94:95], v[94:95]
	s_nop 0
	v_pk_fma_f32 v[92:93], v[92:93], v[92:93], v[94:95]
	v_pk_mul_f32 v[94:95], v[54:55], v[54:55]
	v_pk_add_f32 v[82:83], v[82:83], v[92:93]
	v_pk_mul_f32 v[92:93], v[56:57], v[56:57]
	v_pk_add_f32 v[82:83], v[82:83], v[82:83] op_sel_hi:[0,1]
	v_pk_mov_b32 v[96:97], v[94:95], v[92:93] op_sel:[1,0]
	v_mov_b32_e32 v95, v93
	v_mul_f32_e32 v82, v50, v50
	v_pk_add_f32 v[92:93], v[96:97], v[94:95]
	v_pk_fma_f32 v[94:95], v[50:51], v[50:51], v[82:83] op_sel_hi:[1,1,0]
	v_mul_f32_e32 v82, v52, v52
	v_pk_add_f32 v[92:93], v[92:93], v[92:93] op_sel_hi:[0,1]
	v_pk_fma_f32 v[96:97], v[52:53], v[52:53], v[82:83] op_sel_hi:[1,1,0]
	v_mul_f32_e32 v94, v46, v46
	v_mul_f32_e32 v96, v47, v47
	v_mul_f32_e32 v92, v48, v48
	v_mul_f32_e32 v82, v49, v49
	v_pk_add_f32 v[94:95], v[94:95], v[96:97]
	v_pk_add_f32 v[82:83], v[92:93], v[82:83]
	v_pk_mul_f32 v[92:93], v[44:45], v[44:45]
	v_pk_add_f32 v[82:83], v[94:95], v[82:83]
	v_pk_mul_f32 v[94:95], v[42:43], v[42:43]
	v_pk_add_f32 v[82:83], v[82:83], v[82:83] op_sel_hi:[0,1]
	v_pk_mov_b32 v[96:97], v[94:95], v[92:93] op_sel:[1,0]
	v_mov_b32_e32 v95, v93
	v_mul_f32_e32 v82, v38, v38
	v_pk_add_f32 v[92:93], v[96:97], v[94:95]
	v_pk_fma_f32 v[94:95], v[38:39], v[38:39], v[82:83] op_sel_hi:[1,1,0]
	v_mul_f32_e32 v82, v40, v40
	v_pk_add_f32 v[92:93], v[92:93], v[92:93] op_sel_hi:[0,1]
	v_pk_fma_f32 v[96:97], v[40:41], v[40:41], v[82:83] op_sel_hi:[1,1,0]
	v_mul_f32_e32 v94, v34, v34
	v_mul_f32_e32 v96, v35, v35
	v_mul_f32_e32 v92, v36, v36
	v_mul_f32_e32 v82, v37, v37
	v_pk_add_f32 v[94:95], v[94:95], v[96:97]
	v_pk_add_f32 v[82:83], v[92:93], v[82:83]
	s_nop 0
	v_pk_add_f32 v[82:83], v[94:95], v[82:83]
	s_nop 0
	v_add_f32_e32 v82, v82, v83
	ds_bpermute_b32 v83, v84, v82
	s_waitcnt lgkmcnt(0)
	v_add_f32_e32 v82, v82, v83
	ds_bpermute_b32 v83, v85, v82
	s_waitcnt lgkmcnt(0)
	v_add_f32_e32 v82, v82, v83
	ds_bpermute_b32 v83, v86, v82
	s_waitcnt lgkmcnt(0)
	v_add_f32_e32 v82, v82, v83
	ds_bpermute_b32 v83, v87, v82
	s_waitcnt lgkmcnt(0)
	v_add_f32_e32 v82, v82, v83
	ds_bpermute_b32 v83, v88, v82
	s_waitcnt lgkmcnt(0)
	v_add_f32_e32 v82, v82, v83
	ds_bpermute_b32 v83, v89, v82
	s_waitcnt lgkmcnt(0)
	v_add_f32_e32 v82, v82, v83
	v_fmamk_f32 v82, v82, 0x3a000000, v1
	v_cmp_gt_f32_e32 vcc, s2, v82
	v_mul_f32_e32 v83, 0x4f800000, v82
	s_nop 0
	v_cndmask_b32_e32 v82, v82, v83, vcc
	v_sqrt_f32_e32 v83, v82
	s_nop 0
	v_add_u32_e32 v92, -1, v83
	v_fma_f32 v93, -v92, v83, v82
	v_cmp_ge_f32_e64 s[4:5], 0, v93
	v_add_u32_e32 v93, 1, v83
	s_nop 0
	v_cndmask_b32_e64 v92, v83, v92, s[4:5]
	v_fma_f32 v83, -v93, v83, v82
	v_cmp_lt_f32_e64 s[4:5], 0, v83
	s_nop 1
	v_cndmask_b32_e64 v83, v92, v93, s[4:5]
	v_mul_f32_e32 v92, 0x37800000, v83
	v_cndmask_b32_e32 v83, v83, v92, vcc
	v_cmp_class_f32_e32 vcc, v82, v66
	s_nop 1
	v_cndmask_b32_e32 v82, v83, v82, vcc
	v_div_scale_f32 v83, s[4:5], v82, v82, 1.0
	v_rcp_f32_e32 v92, v83
	s_nop 0
	v_fma_f32 v93, -v83, v92, 1.0
	v_fmac_f32_e32 v92, v93, v92
	v_div_scale_f32 v93, vcc, 1.0, v82, 1.0
	v_mul_f32_e32 v94, v93, v92
	v_fma_f32 v95, -v83, v94, v93
	v_fmac_f32_e32 v94, v95, v92
	v_fma_f32 v83, -v83, v94, v93
	v_div_fmas_f32 v83, v83, v92, v94
	v_div_fixup_f32 v96, v83, v82, 1.0
	v_pk_mul_f32 v[98:99], v[62:63], v[96:97] op_sel_hi:[1,0]
	v_pk_mul_f32 v[62:63], v[64:65], v[96:97] op_sel_hi:[1,0]
	v_lshl_add_u64 v[82:83], s[34:35], 0, v[80:81]
	s_nop 0
	v_pk_mul_f32 v[62:63], v[118:119], v[62:63]
	v_pk_mul_f32 v[64:65], v[116:117], v[98:99]
	v_cvt_pk_bf16_f32 v93, v62, v63
	v_cvt_pk_bf16_f32 v92, v64, v65
	global_store_dwordx2 v[82:83], v[92:93], off offset:-2048
	v_pk_mul_f32 v[98:99], v[58:59], v[96:97] op_sel_hi:[1,0]
	v_pk_mul_f32 v[58:59], v[60:61], v[96:97] op_sel_hi:[1,0]
	s_nop 0
	v_pk_mul_f32 v[60:61], v[120:121], v[98:99]
	v_pk_mul_f32 v[58:59], v[122:123], v[58:59]
	v_cvt_pk_bf16_f32 v92, v60, v61
	v_cvt_pk_bf16_f32 v93, v58, v59
	global_store_dwordx2 v[82:83], v[92:93], off offset:-1536
	v_pk_mul_f32 v[98:99], v[54:55], v[96:97] op_sel_hi:[1,0]
	v_pk_mul_f32 v[54:55], v[56:57], v[96:97] op_sel_hi:[1,0]
	s_nop 0
	v_pk_mul_f32 v[56:57], v[124:125], v[98:99]
	v_pk_mul_f32 v[54:55], v[126:127], v[54:55]
	v_cvt_pk_bf16_f32 v92, v56, v57
	v_cvt_pk_bf16_f32 v93, v54, v55
	global_store_dwordx2 v[82:83], v[92:93], off offset:-1024
	v_pk_mul_f32 v[98:99], v[50:51], v[96:97] op_sel_hi:[1,0]
	v_pk_mul_f32 v[50:51], v[52:53], v[96:97] op_sel_hi:[1,0]
	s_nop 0
	v_pk_mul_f32 v[52:53], v[128:129], v[98:99]
	v_pk_mul_f32 v[50:51], v[130:131], v[50:51]
	v_cvt_pk_bf16_f32 v92, v52, v53
	v_cvt_pk_bf16_f32 v93, v50, v51
	global_store_dwordx2 v[82:83], v[92:93], off offset:-512
	v_pk_mul_f32 v[98:99], v[46:47], v[96:97] op_sel_hi:[1,0]
	v_pk_mul_f32 v[46:47], v[48:49], v[96:97] op_sel_hi:[1,0]
	s_nop 0
	v_pk_mul_f32 v[48:49], v[98:99], v[132:133]
	v_pk_mul_f32 v[46:47], v[46:47], v[134:135]
	v_cvt_pk_bf16_f32 v92, v48, v49
	v_cvt_pk_bf16_f32 v93, v46, v47
	global_store_dwordx2 v[82:83], v[92:93], off
	v_pk_mul_f32 v[98:99], v[42:43], v[96:97] op_sel_hi:[1,0]
	v_pk_mul_f32 v[42:43], v[44:45], v[96:97] op_sel_hi:[1,0]
	s_nop 0
	v_pk_mul_f32 v[44:45], v[98:99], v[136:137]
	v_pk_mul_f32 v[42:43], v[42:43], v[138:139]
	v_cvt_pk_bf16_f32 v92, v44, v45
	v_cvt_pk_bf16_f32 v93, v42, v43
	global_store_dwordx2 v[82:83], v[92:93], off offset:512
	v_pk_mul_f32 v[98:99], v[38:39], v[96:97] op_sel_hi:[1,0]
	v_pk_mul_f32 v[38:39], v[40:41], v[96:97] op_sel_hi:[1,0]
	s_nop 0
	v_pk_mul_f32 v[40:41], v[98:99], v[140:141]
	v_pk_mul_f32 v[38:39], v[38:39], v[142:143]
	v_cvt_pk_bf16_f32 v92, v40, v41
	v_cvt_pk_bf16_f32 v93, v38, v39
	global_store_dwordx2 v[82:83], v[92:93], off offset:1024
	v_pk_mul_f32 v[98:99], v[34:35], v[96:97] op_sel_hi:[1,0]
	v_pk_mul_f32 v[34:35], v[36:37], v[96:97] op_sel_hi:[1,0]
	s_nop 0
	v_pk_mul_f32 v[36:37], v[98:99], v[144:145]
	v_pk_mul_f32 v[34:35], v[34:35], v[146:147]
	v_cvt_pk_bf16_f32 v92, v36, v37
	v_cvt_pk_bf16_f32 v93, v34, v35
	global_store_dwordx2 v[82:83], v[92:93], off offset:1536
	ds_read_b128 v[96:99], v90
	ds_read_b128 v[100:103], v90 offset:16
	ds_read_b128 v[104:107], v90 offset:32
	ds_read_b128 v[108:111], v90 offset:48
	s_waitcnt lgkmcnt(3)
; #define LAS __attribute__((address_space(3)))
; __device__ __forceinline__ void prologue_phase(const Ptrs& P, LAS unsigned char* lds, int vcu, int G, int tid, int lane, int wave) {
;     ...
;         for (int j = 0; j < 8; ++j)
; #pragma unroll
;             for (int i = 0; i < 4; ++i) { const int k = 256 * j + 4 * lane + i; const f32x4 w0 = *(const LAS f32x4*)(wg + k * 8), w1 = *(const LAS f32x4*)(wg + k * 8 + 4); const float hv = v[j][i];
;                 a[0] += hv * w0.x; a[1] += hv * w0.y; a[2] += hv * w0.z; a[3] += hv * w0.w; a[4] += hv * w1.x; a[5] += hv * w1.y; a[6] += hv * w1.z; a[7] += hv * w1.w;
;                 if (i == 3) asm volatile("" ::: "memory"); }
	v_fma_f32 v96, v64, v96, 0
	v_fma_f32 v95, v64, v97, 0
	v_fma_f32 v94, v64, v98, 0
	v_fma_f32 v93, v64, v99, 0
	s_waitcnt lgkmcnt(2)
	v_fma_f32 v92, v64, v100, 0
	v_fma_f32 v83, v64, v101, 0
	v_fma_f32 v82, v64, v102, 0
	v_fma_f32 v64, v64, v103, 0
	s_waitcnt lgkmcnt(1)
	v_fmac_f32_e32 v96, v65, v104
	v_fmac_f32_e32 v95, v65, v105
	ds_read_b128 v[98:101], v90 offset:64
	ds_read_b128 v[102:105], v90 offset:80
	v_fmac_f32_e32 v94, v65, v106
	v_fmac_f32_e32 v93, v65, v107
	s_waitcnt lgkmcnt(2)
	v_fmac_f32_e32 v92, v65, v108
	v_fmac_f32_e32 v83, v65, v109
	v_fmac_f32_e32 v82, v65, v110
	v_fmac_f32_e32 v64, v65, v111
	s_waitcnt lgkmcnt(1)
	v_fmac_f32_e32 v96, v62, v98
	v_fmac_f32_e32 v95, v62, v99
	v_fmac_f32_e32 v94, v62, v100
	v_fmac_f32_e32 v93, v62, v101
	s_waitcnt lgkmcnt(0)
	v_fmac_f32_e32 v92, v62, v102
	v_fmac_f32_e32 v83, v62, v103
	v_fmac_f32_e32 v82, v62, v104
	v_fmac_f32_e32 v64, v62, v105
	ds_read_b128 v[98:101], v90 offset:96
	ds_read_b128 v[102:105], v90 offset:112
	s_waitcnt lgkmcnt(1)
	v_fmac_f32_e32 v96, v63, v98
	v_fmac_f32_e32 v95, v63, v99
	v_fmac_f32_e32 v94, v63, v100
	v_fmac_f32_e32 v93, v63, v101
	s_waitcnt lgkmcnt(0)
	v_fmac_f32_e32 v92, v63, v102
	v_fmac_f32_e32 v83, v63, v103
	v_fmac_f32_e32 v82, v63, v104
	v_fmac_f32_e32 v64, v63, v105
	ds_read_b128 v[98:101], v90 offset:8192
	ds_read_b128 v[102:105], v90 offset:8208
	ds_read_b128 v[106:109], v90 offset:8224
	ds_read_b128 v[110:113], v90 offset:8240
	s_waitcnt lgkmcnt(3)
	v_fmac_f32_e32 v96, v60, v98
	v_fmac_f32_e32 v95, v60, v99
	v_fmac_f32_e32 v94, v60, v100
	v_fmac_f32_e32 v93, v60, v101
	s_waitcnt lgkmcnt(2)
	v_fmac_f32_e32 v92, v60, v102
	v_fmac_f32_e32 v83, v60, v103
	v_fmac_f32_e32 v82, v60, v104
	v_fmac_f32_e32 v64, v60, v105
	s_waitcnt lgkmcnt(1)
	v_fmac_f32_e32 v96, v61, v106
	v_fmac_f32_e32 v95, v61, v107
	v_fmac_f32_e32 v94, v61, v108
	v_fmac_f32_e32 v93, v61, v109
	s_waitcnt lgkmcnt(0)
	v_fmac_f32_e32 v92, v61, v110
	v_fmac_f32_e32 v83, v61, v111
	v_fmac_f32_e32 v82, v61, v112
	v_fmac_f32_e32 v64, v61, v113
	ds_read_b128 v[60:63], v90 offset:8256
	ds_read_b128 v[98:101], v90 offset:8272
	s_waitcnt lgkmcnt(1)
	v_fmac_f32_e32 v96, v58, v60
	v_fmac_f32_e32 v95, v58, v61
	v_fmac_f32_e32 v94, v58, v62
	v_fmac_f32_e32 v93, v58, v63
	s_waitcnt lgkmcnt(0)
	v_fmac_f32_e32 v92, v58, v98
	v_fmac_f32_e32 v83, v58, v99
	v_fmac_f32_e32 v82, v58, v100
	v_fmac_f32_e32 v64, v58, v101
	ds_read_b128 v[60:63], v90 offset:8288
	ds_read_b128 v[98:101], v90 offset:8304
	s_waitcnt lgkmcnt(1)
	v_fmac_f32_e32 v96, v59, v60
	v_fmac_f32_e32 v95, v59, v61
	v_fmac_f32_e32 v94, v59, v62
	v_fmac_f32_e32 v93, v59, v63
	s_waitcnt lgkmcnt(0)
	v_fmac_f32_e32 v92, v59, v98
	v_fmac_f32_e32 v83, v59, v99
	v_fmac_f32_e32 v82, v59, v100
	v_fmac_f32_e32 v64, v59, v101
	ds_read_b128 v[58:61], v90 offset:16384
	ds_read_b128 v[98:101], v90 offset:16400
	ds_read_b128 v[102:105], v90 offset:16416
	ds_read_b128 v[106:109], v90 offset:16432
	s_waitcnt lgkmcnt(3)
	v_fmac_f32_e32 v96, v56, v58
	v_fmac_f32_e32 v95, v56, v59
	v_fmac_f32_e32 v94, v56, v60
	v_fmac_f32_e32 v93, v56, v61
	s_waitcnt lgkmcnt(2)
	v_fmac_f32_e32 v92, v56, v98
	v_fmac_f32_e32 v83, v56, v99
	v_fmac_f32_e32 v82, v56, v100
	v_fmac_f32_e32 v64, v56, v101
	s_waitcnt lgkmcnt(1)
	v_fmac_f32_e32 v96, v57, v102
	v_fmac_f32_e32 v95, v57, v103
	v_fmac_f32_e32 v94, v57, v104
	v_fmac_f32_e32 v93, v57, v105
	s_waitcnt lgkmcnt(0)
	v_fmac_f32_e32 v92, v57, v106
	v_fmac_f32_e32 v83, v57, v107
	v_fmac_f32_e32 v82, v57, v108
	v_fmac_f32_e32 v64, v57, v109
	ds_read_b128 v[56:59], v90 offset:16448
	ds_read_b128 v[60:63], v90 offset:16464
	s_waitcnt lgkmcnt(1)
	v_fmac_f32_e32 v96, v54, v56
	v_fmac_f32_e32 v95, v54, v57
	v_fmac_f32_e32 v94, v54, v58
	v_fmac_f32_e32 v93, v54, v59
	s_waitcnt lgkmcnt(0)
	v_fmac_f32_e32 v92, v54, v60
	v_fmac_f32_e32 v83, v54, v61
	v_fmac_f32_e32 v82, v54, v62
	v_fmac_f32_e32 v64, v54, v63
	ds_read_b128 v[56:59], v90 offset:16480
	ds_read_b128 v[60:63], v90 offset:16496
	s_waitcnt lgkmcnt(1)
	v_fmac_f32_e32 v96, v55, v56
	v_fmac_f32_e32 v95, v55, v57
	v_fmac_f32_e32 v94, v55, v58
	v_fmac_f32_e32 v93, v55, v59
	s_waitcnt lgkmcnt(0)
	v_fmac_f32_e32 v92, v55, v60
	v_fmac_f32_e32 v83, v55, v61
	v_fmac_f32_e32 v82, v55, v62
	v_fmac_f32_e32 v64, v55, v63
	ds_read_b128 v[54:57], v90 offset:24576
	ds_read_b128 v[58:61], v90 offset:24592
	ds_read_b128 v[98:101], v90 offset:24608
	ds_read_b128 v[102:105], v90 offset:24624
	s_waitcnt lgkmcnt(3)
	v_fmac_f32_e32 v96, v52, v54
	v_fmac_f32_e32 v95, v52, v55
	v_fmac_f32_e32 v94, v52, v56
	v_fmac_f32_e32 v93, v52, v57
	s_waitcnt lgkmcnt(2)
	v_fmac_f32_e32 v92, v52, v58
	v_fmac_f32_e32 v83, v52, v59
	v_fmac_f32_e32 v82, v52, v60
	v_fmac_f32_e32 v64, v52, v61
	s_waitcnt lgkmcnt(1)
	v_fmac_f32_e32 v96, v53, v98
	v_fmac_f32_e32 v95, v53, v99
	v_fmac_f32_e32 v94, v53, v100
	v_fmac_f32_e32 v93, v53, v101
	s_waitcnt lgkmcnt(0)
	v_fmac_f32_e32 v92, v53, v102
	v_fmac_f32_e32 v83, v53, v103
	v_fmac_f32_e32 v82, v53, v104
	v_fmac_f32_e32 v64, v53, v105
	ds_read_b128 v[52:55], v90 offset:24640
	ds_read_b128 v[56:59], v90 offset:24656
	s_waitcnt lgkmcnt(1)
	v_fmac_f32_e32 v96, v50, v52
	v_fmac_f32_e32 v95, v50, v53
	v_fmac_f32_e32 v94, v50, v54
	v_fmac_f32_e32 v93, v50, v55
	s_waitcnt lgkmcnt(0)
	v_fmac_f32_e32 v92, v50, v56
	v_fmac_f32_e32 v83, v50, v57
	v_fmac_f32_e32 v82, v50, v58
	v_fmac_f32_e32 v64, v50, v59
	ds_read_b128 v[52:55], v90 offset:24672
	ds_read_b128 v[56:59], v90 offset:24688
	s_waitcnt lgkmcnt(1)
	v_fmac_f32_e32 v96, v51, v52
	v_fmac_f32_e32 v95, v51, v53
	v_fmac_f32_e32 v94, v51, v54
	v_fmac_f32_e32 v93, v51, v55
	s_waitcnt lgkmcnt(0)
; #define LAS __attribute__((address_space(3)))
; __device__ __forceinline__ void prologue_phase(const Ptrs& P, LAS unsigned char* lds, int vcu, int G, int tid, int lane, int wave) {
;     ...
;         for (int j = 0; j < 8; ++j)
; #pragma unroll
;             for (int i = 0; i < 4; ++i) { const int k = 256 * j + 4 * lane + i; const f32x4 w0 = *(const LAS f32x4*)(wg + k * 8), w1 = *(const LAS f32x4*)(wg + k * 8 + 4); const float hv = v[j][i];
;                 a[0] += hv * w0.x; a[1] += hv * w0.y; a[2] += hv * w0.z; a[3] += hv * w0.w; a[4] += hv * w1.x; a[5] += hv * w1.y; a[6] += hv * w1.z; a[7] += hv * w1.w;
;                 if (i == 3) asm volatile("" ::: "memory"); }
	v_fmac_f32_e32 v92, v51, v56
	v_fmac_f32_e32 v83, v51, v57
	v_fmac_f32_e32 v82, v51, v58
	v_fmac_f32_e32 v64, v51, v59
	ds_read_b128 v[50:53], v90 offset:32768
	ds_read_b128 v[54:57], v90 offset:32784
	ds_read_b128 v[58:61], v90 offset:32800
	ds_read_b128 v[98:101], v90 offset:32816
	s_waitcnt lgkmcnt(3)
	v_fmac_f32_e32 v96, v48, v50
	v_fmac_f32_e32 v95, v48, v51
	v_fmac_f32_e32 v94, v48, v52
	v_fmac_f32_e32 v93, v48, v53
	s_waitcnt lgkmcnt(2)
	v_fmac_f32_e32 v92, v48, v54
	v_fmac_f32_e32 v83, v48, v55
	v_fmac_f32_e32 v82, v48, v56
	v_fmac_f32_e32 v64, v48, v57
	s_waitcnt lgkmcnt(1)
	v_fmac_f32_e32 v96, v49, v58
	v_fmac_f32_e32 v95, v49, v59
	v_fmac_f32_e32 v94, v49, v60
	v_fmac_f32_e32 v93, v49, v61
	s_waitcnt lgkmcnt(0)
	v_fmac_f32_e32 v92, v49, v98
	v_fmac_f32_e32 v83, v49, v99
	v_fmac_f32_e32 v82, v49, v100
	v_fmac_f32_e32 v64, v49, v101
	ds_read_b128 v[48:51], v90 offset:32832
	ds_read_b128 v[52:55], v90 offset:32848
	s_waitcnt lgkmcnt(1)
	v_fmac_f32_e32 v96, v46, v48
	v_fmac_f32_e32 v95, v46, v49
	v_fmac_f32_e32 v94, v46, v50
	v_fmac_f32_e32 v93, v46, v51
	s_waitcnt lgkmcnt(0)
	v_fmac_f32_e32 v92, v46, v52
	v_fmac_f32_e32 v83, v46, v53
	v_fmac_f32_e32 v82, v46, v54
	v_fmac_f32_e32 v64, v46, v55
	ds_read_b128 v[48:51], v90 offset:32864
	ds_read_b128 v[52:55], v90 offset:32880
	s_waitcnt lgkmcnt(1)
	v_fmac_f32_e32 v96, v47, v48
	v_fmac_f32_e32 v95, v47, v49
	v_fmac_f32_e32 v94, v47, v50
	v_fmac_f32_e32 v93, v47, v51
	s_waitcnt lgkmcnt(0)
	v_fmac_f32_e32 v92, v47, v52
	v_fmac_f32_e32 v83, v47, v53
	v_fmac_f32_e32 v82, v47, v54
	v_fmac_f32_e32 v64, v47, v55
	ds_read_b128 v[46:49], v90 offset:40960
	ds_read_b128 v[50:53], v90 offset:40976
	ds_read_b128 v[54:57], v90 offset:40992
	ds_read_b128 v[58:61], v90 offset:41008
	s_waitcnt lgkmcnt(3)
	v_fmac_f32_e32 v96, v44, v46
	v_fmac_f32_e32 v95, v44, v47
	v_fmac_f32_e32 v94, v44, v48
	v_fmac_f32_e32 v93, v44, v49
	s_waitcnt lgkmcnt(2)
	v_fmac_f32_e32 v92, v44, v50
	v_fmac_f32_e32 v83, v44, v51
	v_fmac_f32_e32 v82, v44, v52
	v_fmac_f32_e32 v64, v44, v53
	s_waitcnt lgkmcnt(1)
	v_fmac_f32_e32 v96, v45, v54
	v_fmac_f32_e32 v95, v45, v55
	v_fmac_f32_e32 v94, v45, v56
	v_fmac_f32_e32 v93, v45, v57
	s_waitcnt lgkmcnt(0)
	v_fmac_f32_e32 v92, v45, v58
	v_fmac_f32_e32 v83, v45, v59
	v_fmac_f32_e32 v82, v45, v60
	v_fmac_f32_e32 v64, v45, v61
	ds_read_b128 v[44:47], v90 offset:41024
	ds_read_b128 v[48:51], v90 offset:41040
	s_waitcnt lgkmcnt(1)
	v_fmac_f32_e32 v96, v42, v44
	v_fmac_f32_e32 v95, v42, v45
	v_fmac_f32_e32 v94, v42, v46
	v_fmac_f32_e32 v93, v42, v47
	s_waitcnt lgkmcnt(0)
	v_fmac_f32_e32 v92, v42, v48
	v_fmac_f32_e32 v83, v42, v49
	v_fmac_f32_e32 v82, v42, v50
	v_fmac_f32_e32 v64, v42, v51
	ds_read_b128 v[44:47], v90 offset:41056
	ds_read_b128 v[48:51], v90 offset:41072
	s_waitcnt lgkmcnt(1)
	v_fmac_f32_e32 v96, v43, v44
	v_fmac_f32_e32 v95, v43, v45
	v_fmac_f32_e32 v94, v43, v46
	v_fmac_f32_e32 v93, v43, v47
	s_waitcnt lgkmcnt(0)
	v_fmac_f32_e32 v92, v43, v48
	v_fmac_f32_e32 v83, v43, v49
	v_fmac_f32_e32 v82, v43, v50
	v_fmac_f32_e32 v64, v43, v51
	ds_read_b128 v[42:45], v90 offset:49152
	ds_read_b128 v[46:49], v90 offset:49168
	ds_read_b128 v[50:53], v90 offset:49184
	ds_read_b128 v[54:57], v90 offset:49200
	s_waitcnt lgkmcnt(3)
	v_fmac_f32_e32 v96, v40, v42
	v_fmac_f32_e32 v95, v40, v43
	v_fmac_f32_e32 v94, v40, v44
	v_fmac_f32_e32 v93, v40, v45
	s_waitcnt lgkmcnt(2)
	v_fmac_f32_e32 v92, v40, v46
	v_fmac_f32_e32 v83, v40, v47
	v_fmac_f32_e32 v82, v40, v48
	v_fmac_f32_e32 v64, v40, v49
	s_waitcnt lgkmcnt(1)
	v_fmac_f32_e32 v96, v41, v50
	v_fmac_f32_e32 v95, v41, v51
	v_fmac_f32_e32 v94, v41, v52
	v_fmac_f32_e32 v93, v41, v53
	s_waitcnt lgkmcnt(0)
	v_fmac_f32_e32 v92, v41, v54
	v_fmac_f32_e32 v83, v41, v55
	v_fmac_f32_e32 v82, v41, v56
	v_fmac_f32_e32 v64, v41, v57
	ds_read_b128 v[40:43], v90 offset:49216
	ds_read_b128 v[44:47], v90 offset:49232
	s_waitcnt lgkmcnt(1)
	v_fmac_f32_e32 v96, v38, v40
	v_fmac_f32_e32 v95, v38, v41
	v_fmac_f32_e32 v94, v38, v42
	v_fmac_f32_e32 v93, v38, v43
	s_waitcnt lgkmcnt(0)
	v_fmac_f32_e32 v92, v38, v44
	v_fmac_f32_e32 v83, v38, v45
	v_fmac_f32_e32 v82, v38, v46
	v_fmac_f32_e32 v64, v38, v47
	ds_read_b128 v[40:43], v90 offset:49248
	ds_read_b128 v[44:47], v90 offset:49264
	s_waitcnt lgkmcnt(1)
	v_fmac_f32_e32 v96, v39, v40
	v_fmac_f32_e32 v95, v39, v41
	v_fmac_f32_e32 v94, v39, v42
	v_fmac_f32_e32 v93, v39, v43
	s_waitcnt lgkmcnt(0)
	v_fmac_f32_e32 v92, v39, v44
	v_fmac_f32_e32 v83, v39, v45
	v_fmac_f32_e32 v82, v39, v46
	v_fmac_f32_e32 v64, v39, v47
	ds_read_b128 v[38:41], v90 offset:57344
	ds_read_b128 v[42:45], v90 offset:57360
	ds_read_b128 v[46:49], v90 offset:57376
	ds_read_b128 v[50:53], v90 offset:57392
	s_waitcnt lgkmcnt(3)
	v_fmac_f32_e32 v96, v36, v38
	v_fmac_f32_e32 v95, v36, v39
	v_fmac_f32_e32 v94, v36, v40
	v_fmac_f32_e32 v93, v36, v41
	s_waitcnt lgkmcnt(2)
	v_fmac_f32_e32 v92, v36, v42
	v_fmac_f32_e32 v83, v36, v43
	v_fmac_f32_e32 v82, v36, v44
	v_fmac_f32_e32 v64, v36, v45
	s_waitcnt lgkmcnt(1)
	v_fmac_f32_e32 v96, v37, v46
	v_fmac_f32_e32 v95, v37, v47
	v_fmac_f32_e32 v94, v37, v48
	v_fmac_f32_e32 v93, v37, v49
	s_waitcnt lgkmcnt(0)
	v_fmac_f32_e32 v92, v37, v50
	v_fmac_f32_e32 v83, v37, v51
	v_fmac_f32_e32 v82, v37, v52
	v_fmac_f32_e32 v64, v37, v53
	ds_read_b128 v[36:39], v90 offset:57408
	ds_read_b128 v[40:43], v90 offset:57424
	s_waitcnt lgkmcnt(1)
	v_fmac_f32_e32 v96, v34, v36
	v_fmac_f32_e32 v95, v34, v37
	v_fmac_f32_e32 v94, v34, v38
	v_fmac_f32_e32 v93, v34, v39
	s_waitcnt lgkmcnt(0)
; #define LAS __attribute__((address_space(3)))
; __device__ __forceinline__ void prologue_phase(const Ptrs& P, LAS unsigned char* lds, int vcu, int G, int tid, int lane, int wave) {
;     ...
;         for (int j = 0; j < 8; ++j)
; #pragma unroll
;             for (int i = 0; i < 4; ++i) { const int k = 256 * j + 4 * lane + i; const f32x4 w0 = *(const LAS f32x4*)(wg + k * 8), w1 = *(const LAS f32x4*)(wg + k * 8 + 4); const float hv = v[j][i];
;                 a[0] += hv * w0.x; a[1] += hv * w0.y; a[2] += hv * w0.z; a[3] += hv * w0.w; a[4] += hv * w1.x; a[5] += hv * w1.y; a[6] += hv * w1.z; a[7] += hv * w1.w;
;                 if (i == 3) asm volatile("" ::: "memory"); }
; #pragma unroll
;         for (int q = 0; q < 8; ++q) a[q] = wave_sum(a[q]);
;         if (lane == 0) {
; #pragma unroll
;             for (int q = 0; q < 8; ++q) gates[(size_t)m * 8 + q] = a[q] + P.in[3][q]; }
	v_fmac_f32_e32 v92, v34, v40
	v_fmac_f32_e32 v83, v34, v41
	v_fmac_f32_e32 v82, v34, v42
	v_fmac_f32_e32 v64, v34, v43
	ds_read_b128 v[36:39], v90 offset:57440
	ds_read_b128 v[40:43], v90 offset:57456
	s_waitcnt lgkmcnt(1)
	v_fmac_f32_e32 v96, v35, v36
	v_fmac_f32_e32 v95, v35, v37
	v_fmac_f32_e32 v94, v35, v38
	v_fmac_f32_e32 v93, v35, v39
	s_waitcnt lgkmcnt(0)
	v_fmac_f32_e32 v92, v35, v40
	v_fmac_f32_e32 v83, v35, v41
	v_fmac_f32_e32 v82, v35, v42
	v_fmac_f32_e32 v64, v35, v43
	ds_bpermute_b32 v34, v84, v96
	ds_bpermute_b32 v36, v84, v95
	ds_bpermute_b32 v38, v84, v94
	ds_bpermute_b32 v40, v84, v93
	ds_bpermute_b32 v42, v84, v92
	ds_bpermute_b32 v44, v84, v83
	ds_bpermute_b32 v46, v84, v82
	ds_bpermute_b32 v48, v84, v64
	s_waitcnt lgkmcnt(7)
	v_add_f32_e32 v34, v96, v34
	s_waitcnt lgkmcnt(6)
	v_add_f32_e32 v36, v95, v36
	s_waitcnt lgkmcnt(5)
	v_add_f32_e32 v38, v94, v38
	s_waitcnt lgkmcnt(4)
	v_add_f32_e32 v40, v93, v40
	s_waitcnt lgkmcnt(3)
	v_add_f32_e32 v42, v92, v42
	s_waitcnt lgkmcnt(2)
	v_add_f32_e32 v44, v83, v44
	s_waitcnt lgkmcnt(1)
	v_add_f32_e32 v46, v82, v46
	s_waitcnt lgkmcnt(0)
	v_add_f32_e32 v48, v64, v48
	ds_bpermute_b32 v35, v85, v34
	ds_bpermute_b32 v37, v85, v36
	ds_bpermute_b32 v39, v85, v38
	ds_bpermute_b32 v41, v85, v40
	ds_bpermute_b32 v43, v85, v42
	ds_bpermute_b32 v45, v85, v44
	ds_bpermute_b32 v47, v85, v46
	ds_bpermute_b32 v49, v85, v48
	s_waitcnt lgkmcnt(7)
	v_add_f32_e32 v34, v34, v35
	s_waitcnt lgkmcnt(6)
	v_add_f32_e32 v36, v36, v37
	s_waitcnt lgkmcnt(5)
	v_add_f32_e32 v38, v38, v39
	s_waitcnt lgkmcnt(4)
	v_add_f32_e32 v40, v40, v41
	s_waitcnt lgkmcnt(3)
	v_add_f32_e32 v42, v42, v43
	s_waitcnt lgkmcnt(2)
	v_add_f32_e32 v44, v44, v45
	s_waitcnt lgkmcnt(1)
	v_add_f32_e32 v46, v46, v47
	s_waitcnt lgkmcnt(0)
	v_add_f32_e32 v48, v48, v49
	ds_bpermute_b32 v35, v86, v34
	ds_bpermute_b32 v37, v86, v36
	ds_bpermute_b32 v39, v86, v38
	ds_bpermute_b32 v41, v86, v40
	ds_bpermute_b32 v43, v86, v42
	ds_bpermute_b32 v45, v86, v44
	ds_bpermute_b32 v47, v86, v46
	ds_bpermute_b32 v49, v86, v48
	s_waitcnt lgkmcnt(7)
	v_add_f32_e32 v34, v34, v35
	s_waitcnt lgkmcnt(6)
	v_add_f32_e32 v36, v36, v37
	s_waitcnt lgkmcnt(5)
	v_add_f32_e32 v38, v38, v39
	s_waitcnt lgkmcnt(4)
	v_add_f32_e32 v40, v40, v41
	s_waitcnt lgkmcnt(3)
	v_add_f32_e32 v42, v42, v43
	s_waitcnt lgkmcnt(2)
	v_add_f32_e32 v44, v44, v45
	s_waitcnt lgkmcnt(1)
	v_add_f32_e32 v46, v46, v47
	s_waitcnt lgkmcnt(0)
	v_add_f32_e32 v48, v48, v49
	ds_bpermute_b32 v35, v87, v34
	ds_bpermute_b32 v37, v87, v36
	ds_bpermute_b32 v39, v87, v38
	ds_bpermute_b32 v41, v87, v40
	ds_bpermute_b32 v43, v87, v42
	ds_bpermute_b32 v45, v87, v44
	ds_bpermute_b32 v47, v87, v46
	ds_bpermute_b32 v49, v87, v48
	s_waitcnt lgkmcnt(7)
	v_add_f32_e32 v34, v34, v35
	s_waitcnt lgkmcnt(6)
	v_add_f32_e32 v36, v36, v37
	s_waitcnt lgkmcnt(5)
	v_add_f32_e32 v38, v38, v39
	s_waitcnt lgkmcnt(4)
	v_add_f32_e32 v40, v40, v41
	s_waitcnt lgkmcnt(3)
	v_add_f32_e32 v42, v42, v43
	s_waitcnt lgkmcnt(2)
	v_add_f32_e32 v44, v44, v45
	s_waitcnt lgkmcnt(1)
	v_add_f32_e32 v46, v46, v47
	s_waitcnt lgkmcnt(0)
	v_add_f32_e32 v48, v48, v49
	ds_bpermute_b32 v35, v88, v34
	ds_bpermute_b32 v37, v88, v36
	ds_bpermute_b32 v39, v88, v38
	ds_bpermute_b32 v41, v88, v40
	ds_bpermute_b32 v43, v88, v42
	ds_bpermute_b32 v45, v88, v44
	ds_bpermute_b32 v47, v88, v46
	ds_bpermute_b32 v49, v88, v48
	s_waitcnt lgkmcnt(7)
	v_add_f32_e32 v34, v34, v35
	s_waitcnt lgkmcnt(6)
	v_add_f32_e32 v36, v36, v37
	s_waitcnt lgkmcnt(5)
	v_add_f32_e32 v38, v38, v39
	s_waitcnt lgkmcnt(4)
	v_add_f32_e32 v40, v40, v41
	s_waitcnt lgkmcnt(3)
	v_add_f32_e32 v42, v42, v43
	s_waitcnt lgkmcnt(2)
	v_add_f32_e32 v44, v44, v45
	s_waitcnt lgkmcnt(1)
	v_add_f32_e32 v46, v46, v47
	s_waitcnt lgkmcnt(0)
	v_add_f32_e32 v48, v48, v49
	ds_bpermute_b32 v35, v89, v34
	ds_bpermute_b32 v37, v89, v36
	ds_bpermute_b32 v39, v89, v38
	ds_bpermute_b32 v41, v89, v40
	ds_bpermute_b32 v43, v89, v42
	ds_bpermute_b32 v45, v89, v44
	ds_bpermute_b32 v47, v89, v46
	ds_bpermute_b32 v49, v89, v48
	s_and_saveexec_b64 s[4:5], s[0:1]
	s_cbranch_execz .LBB0_51
	global_load_dword v50, v67, s[26:27]
	s_waitcnt lgkmcnt(7)
	v_add_f32_e32 v34, v34, v35
	s_add_u32 s18, s34, s8
	s_addc_u32 s19, s35, s9
	s_waitcnt lgkmcnt(6)
	v_add_f32_e32 v35, v36, v37
	s_waitcnt vmcnt(0)
	v_add_f32_e32 v34, v34, v50
	global_store_dword v91, v34, s[18:19]
	global_load_dword v34, v67, s[26:27] offset:4
	s_waitcnt vmcnt(0)
	v_add_f32_e32 v34, v35, v34
	global_store_dword v91, v34, s[18:19] offset:4
	global_load_dword v34, v67, s[26:27] offset:8
	s_waitcnt lgkmcnt(5)
	v_add_f32_e32 v35, v38, v39
	s_waitcnt vmcnt(0)
	v_add_f32_e32 v34, v35, v34
	global_store_dword v91, v34, s[18:19] offset:8
	global_load_dword v34, v67, s[26:27] offset:12
	s_waitcnt lgkmcnt(4)
	v_add_f32_e32 v35, v40, v41
	s_waitcnt vmcnt(0)
	v_add_f32_e32 v34, v35, v34
	global_store_dword v91, v34, s[18:19] offset:12
	global_load_dword v34, v67, s[26:27] offset:16
	s_waitcnt lgkmcnt(3)
	v_add_f32_e32 v35, v42, v43
	s_waitcnt vmcnt(0)
	v_add_f32_e32 v34, v35, v34
	global_store_dword v91, v34, s[18:19] offset:16
	global_load_dword v34, v67, s[26:27] offset:20
	s_waitcnt lgkmcnt(2)
	v_add_f32_e32 v35, v44, v45
	s_waitcnt vmcnt(0)
	v_add_f32_e32 v34, v35, v34
	global_store_dword v91, v34, s[18:19] offset:20
	global_load_dword v34, v67, s[26:27] offset:24
	s_waitcnt lgkmcnt(1)
	v_add_f32_e32 v35, v46, v47
	s_waitcnt vmcnt(0)
	v_add_f32_e32 v34, v35, v34
	global_store_dword v91, v34, s[18:19] offset:24
	global_load_dword v34, v67, s[26:27] offset:28
	s_waitcnt lgkmcnt(0)
	v_add_f32_e32 v35, v48, v49
	s_waitcnt vmcnt(0)
	v_add_f32_e32 v34, v35, v34
	global_store_dword v91, v34, s[18:19] offset:28
	s_branch .LBB0_51
